# softmax row-max cross-lane reduction via permlane16/32 swap instead of LDS bpermute
# baseline (speedup 1.0000x reference)
; __device__ __forceinline__ void attn_unit(const Args& c, int l, int b, int h, int qb, float lam, float lam_init, LAS unsigned char* lds) {
;     ...
;             float mx = -INFINITY;
; #pragma unroll
;             for (int kb = 0; kb < 8; ++kb)
; #pragma unroll
;                 for (int e = 0; e < 4; ++e) mx = fmaxf(mx, s[kb][e]);
;             mx = fmaxf(mx, __shfl_xor(mx, 16)); mx = fmaxf(mx, __shfl_xor(mx, 32));
;             const float mnew = fmaxf(mrow[m], mx);
;             const float alpha = __builtin_amdgcn_exp2f(mrow[m] - mnew);
;             mrow[m] = mnew;
;             float ps = 0.f;
; #pragma unroll
;             for (int kb = 0; kb < 8; ++kb)
; #pragma unroll
;                 for (int e = 0; e < 4; ++e) { s[kb][e] = __builtin_amdgcn_exp2f(s[kb][e] - mnew); ps += s[kb][e]; }
;             lrow[m] = lrow[m] * alpha + ps;
.LBB0_249:
	v_max3_f32 v146, v114, s23, v115
	v_max3_f32 v146, v146, v116, v117
	v_max3_f32 v146, v146, v118, v119
	v_max3_f32 v146, v146, v120, v121
	v_max3_f32 v146, v146, v122, v123
	v_max3_f32 v146, v146, v124, v125
	v_max3_f32 v146, v146, v126, v127
	v_max3_f32 v146, v146, v128, v129
	v_max3_f32 v146, v146, v130, v131
	v_max3_f32 v146, v146, v132, v133
	v_max3_f32 v146, v146, v134, v135
	v_max3_f32 v146, v146, v136, v137
	v_max3_f32 v146, v146, v138, v139
	v_max3_f32 v146, v146, v140, v141
	v_max3_f32 v146, v146, v142, v143
	v_max3_f32 v146, v146, v144, v145
	v_mov_b32_e32 v147, v146
	s_nop 1
	v_permlane16_swap_b32_e32 v146, v147
	v_max_f32_e32 v146, v146, v147
	v_mov_b32_e32 v147, v146
	s_nop 1
	v_permlane32_swap_b32_e32 v146, v147
	v_max3_f32 v213, v148, v146, v147
	v_sub_f32_e32 v146, v148, v213
	v_exp_f32_e32 v190, v146
	s_nop 0
	v_cmp_neq_f32_e32 vcc, 1.0, v190
	s_cbranch_vccz .LBB0_251
	v_pk_mul_f32 v[48:49], v[48:49], v[190:191] op_sel_hi:[1,0]
	v_pk_mul_f32 v[46:47], v[46:47], v[190:191] op_sel_hi:[1,0]
	v_pk_mul_f32 v[40:41], v[40:41], v[190:191] op_sel_hi:[1,0]
	v_pk_mul_f32 v[38:39], v[38:39], v[190:191] op_sel_hi:[1,0]
	v_pk_mul_f32 v[32:33], v[32:33], v[190:191] op_sel_hi:[1,0]
	v_pk_mul_f32 v[30:31], v[30:31], v[190:191] op_sel_hi:[1,0]
	v_pk_mul_f32 v[64:65], v[64:65], v[190:191] op_sel_hi:[1,0]
	v_pk_mul_f32 v[62:63], v[62:63], v[190:191] op_sel_hi:[1,0]
	v_pk_mul_f32 v[24:25], v[24:25], v[190:191] op_sel_hi:[1,0]
	v_pk_mul_f32 v[22:23], v[22:23], v[190:191] op_sel_hi:[1,0]
	v_pk_mul_f32 v[16:17], v[16:17], v[190:191] op_sel_hi:[1,0]
	v_pk_mul_f32 v[14:15], v[14:15], v[190:191] op_sel_hi:[1,0]
	v_pk_mul_f32 v[8:9], v[8:9], v[190:191] op_sel_hi:[1,0]
	v_pk_mul_f32 v[6:7], v[6:7], v[190:191] op_sel_hi:[1,0]
	v_pk_mul_f32 v[112:113], v[112:113], v[190:191] op_sel_hi:[1,0]
	v_pk_mul_f32 v[110:111], v[110:111], v[190:191] op_sel_hi:[1,0]

; __device__ __forceinline__ void attn_unit(const Args& c, int l, int b, int h, int qb, float lam, float lam_init, LAS unsigned char* lds) {
;     ...
;             float mx = -INFINITY;
; #pragma unroll
;             for (int kb = 0; kb < 8; ++kb)
; #pragma unroll
;                 for (int e = 0; e < 4; ++e) mx = fmaxf(mx, s[kb][e]);
;             mx = fmaxf(mx, __shfl_xor(mx, 16)); mx = fmaxf(mx, __shfl_xor(mx, 32));
;             const float mnew = fmaxf(mrow[m], mx);
;             const float alpha = __builtin_amdgcn_exp2f(mrow[m] - mnew);
;             mrow[m] = mnew;
;             float ps = 0.f;
; #pragma unroll
;             for (int kb = 0; kb < 8; ++kb)
; #pragma unroll
;                 for (int e = 0; e < 4; ++e) { s[kb][e] = __builtin_amdgcn_exp2f(s[kb][e] - mnew); ps += s[kb][e]; }
;             lrow[m] = lrow[m] * alpha + ps;
.LBB0_253:
	s_nop 4
	v_max3_f32 v180, v174, s23, v175
	v_max3_f32 v180, v180, v176, v177
	v_max3_f32 v180, v180, v170, v171
	v_max3_f32 v180, v180, v172, v173
	v_max3_f32 v180, v180, v166, v167
	v_max3_f32 v180, v180, v168, v169
	v_max3_f32 v180, v180, v162, v163
	v_max3_f32 v180, v180, v164, v165
	v_max3_f32 v180, v180, v158, v159
	v_max3_f32 v180, v180, v160, v161
	v_max3_f32 v180, v180, v154, v155
	v_max3_f32 v180, v180, v156, v157
	v_max3_f32 v180, v180, v150, v151
	v_max3_f32 v180, v180, v152, v153
	v_max3_f32 v180, v180, v146, v147
	v_max3_f32 v180, v180, v148, v149
	v_mov_b32_e32 v181, v180
	s_nop 1
	v_permlane16_swap_b32_e32 v180, v181
	v_max_f32_e32 v180, v180, v181
	v_mov_b32_e32 v181, v180
	s_nop 1
	v_permlane32_swap_b32_e32 v180, v181
	v_max3_f32 v214, v192, v180, v181
	v_sub_f32_e32 v180, v192, v214
	v_exp_f32_e32 v192, v180
	s_nop 0
	v_cmp_neq_f32_e32 vcc, 1.0, v192
	s_cbranch_vccz .LBB0_255
	v_pk_mul_f32 v[44:45], v[44:45], v[192:193] op_sel_hi:[1,0]
	v_pk_mul_f32 v[42:43], v[42:43], v[192:193] op_sel_hi:[1,0]
	v_pk_mul_f32 v[36:37], v[36:37], v[192:193] op_sel_hi:[1,0]
	v_pk_mul_f32 v[34:35], v[34:35], v[192:193] op_sel_hi:[1,0]
	v_pk_mul_f32 v[28:29], v[28:29], v[192:193] op_sel_hi:[1,0]
	v_pk_mul_f32 v[26:27], v[26:27], v[192:193] op_sel_hi:[1,0]
	v_pk_mul_f32 v[60:61], v[60:61], v[192:193] op_sel_hi:[1,0]
	v_pk_mul_f32 v[58:59], v[58:59], v[192:193] op_sel_hi:[1,0]
	v_pk_mul_f32 v[20:21], v[20:21], v[192:193] op_sel_hi:[1,0]
	v_pk_mul_f32 v[18:19], v[18:19], v[192:193] op_sel_hi:[1,0]
	v_pk_mul_f32 v[12:13], v[12:13], v[192:193] op_sel_hi:[1,0]
	v_pk_mul_f32 v[10:11], v[10:11], v[192:193] op_sel_hi:[1,0]
	v_pk_mul_f32 v[4:5], v[4:5], v[192:193] op_sel_hi:[1,0]
	v_pk_mul_f32 v[2:3], v[2:3], v[192:193] op_sel_hi:[1,0]
	v_pk_mul_f32 v[108:109], v[108:109], v[192:193] op_sel_hi:[1,0]
	v_pk_mul_f32 v[106:107], v[106:107], v[192:193] op_sel_hi:[1,0]
